# filter_mlp: all layer weights prefetched into registers (161 loads issued up front, third layer's during the first), the three k loops fully unrolled as the same fma chains; pointer fetches via ds_rea
# speedup vs baseline: 1.0057x; 1.0036x over previous
; #define TIDX tid_opaque()
; __device__ __forceinline__ const void* ldp(int i) {
;     const unsigned long long v = *(const volatile unsigned long long*)(g_smem + PTR_OFF + 8 * i);
;     const unsigned lo = __builtin_amdgcn_readfirstlane((unsigned)v), hi = __builtin_amdgcn_readfirstlane((unsigned)(v >> 32));
;     return (const void*)(const __attribute__((address_space(1))) void*)(((unsigned long long)hi << 32) | lo);
; }
; __device__ void filter_mlp_phase(unsigned char* smem, int l) {
;     float* zz = (float*)smem;
;     float* ha = zz + 8 * 36;
;     float* hb = ha + 8 * 64;
;     const float* w1 = ((const float*)ldp(9)) + (size_t)l * 33 * 64; const float* b1 = ((const float*)ldp(10)) + l * 64; const float* w2 = ((const float*)ldp(11)) + (size_t)l * 64 * 64; const float* b2 = ((const float*)ldp(12)) + l * 64;
;     const float* w3 = ((const float*)ldp(13)) + (size_t)l * 64 * 64; const float* b3 = ((const float*)ldp(14)) + l * 64; const float* fr = ((const float*)ldp(15)) + l * 64;
;     float* hdn = (float*)(((unsigned char*)ldp(38)) + OFF_HDN);
;     const int tid = TIDX, u = tid & 63, ps = tid >> 6;
.LBB0_381:
	s_add_i32 s0, 0, 0x23e48
	s_cmp_lg_u32 s0, -1
	s_cselect_b32 s0, s0, 0
	s_cselect_b32 s1, s41, 0
	v_mov_b32_e32 v0, s0
	s_add_i32 s0, 0, 0x23e50
	s_cmp_lg_u32 s0, -1
	s_cselect_b32 s0, s0, 0
	v_mov_b32_e32 v1, s1
	s_cselect_b32 s1, s41, 0
	v_mov_b32_e32 v2, s0
	s_add_i32 s0, 0, 0x23e58
	s_cmp_lg_u32 s0, -1
	s_cselect_b32 s0, s0, 0
	v_mov_b32_e32 v3, s1
	s_cselect_b32 s1, s41, 0
	v_mov_b32_e32 v4, s0
	s_add_i32 s0, 0, 0x23e60
	s_cmp_lg_u32 s0, -1
	v_mov_b32_e32 v5, s1
	s_cselect_b32 s0, s0, 0
	ds_read_b64 v[0:1], v0
	s_waitcnt lgkmcnt(0)
	s_cselect_b32 s1, s41, 0
	ds_read_b64 v[2:3], v2
	s_waitcnt lgkmcnt(0)
	v_readfirstlane_b32 s14, v1
	ds_read_b64 v[6:7], v4
	s_waitcnt lgkmcnt(0)
	v_mov_b32_e32 v4, s0
	s_add_i32 s0, 0, 0x23e68
	s_cmp_lg_u32 s0, -1
	v_mov_b32_e32 v5, s1
	s_cselect_b32 s0, s0, 0
	ds_read_b64 v[8:9], v4
	s_waitcnt lgkmcnt(0)
	s_cselect_b32 s1, s41, 0
	v_mov_b32_e32 v4, s0
	s_add_i32 s0, 0, 0x23e70
	s_cmp_lg_u32 s0, -1
	v_mov_b32_e32 v5, s1
	s_cselect_b32 s0, s0, 0
	ds_read_b64 v[10:11], v4
	s_waitcnt lgkmcnt(0)
	s_cselect_b32 s1, s41, 0
	v_mov_b32_e32 v4, s0
	s_add_i32 s0, 0, 0x23e78
	s_cmp_lg_u32 s0, -1
	v_mov_b32_e32 v5, s1
	s_cselect_b32 s0, s0, 0
	s_cselect_b32 s1, s41, 0
	s_cmp_lg_u32 s40, -1
	ds_read_b64 v[12:13], v4
	s_waitcnt lgkmcnt(0)
	v_mov_b32_e32 v4, s0
	v_mov_b32_e32 v5, s1
	s_cselect_b32 s0, s40, 0
	s_cselect_b32 s1, s41, 0
	ds_read_b64 v[14:15], v4
	s_waitcnt lgkmcnt(0)
	v_mov_b32_e32 v4, s0
	v_mov_b32_e32 v5, s1
	ds_read_b64 v[16:17], v4
	s_waitcnt lgkmcnt(0)
	v_readlane_b32 s0, v254, 48
	v_readlane_b32 s1, v254, 49
	v_mov_b32_e32 v4, v234
	s_andn2_b64 vcc, exec, s[0:1]
	v_readfirstlane_b32 s15, v0
	v_readfirstlane_b32 s0, v3
	v_readfirstlane_b32 s1, v2
	s_waitcnt lgkmcnt(0)
	v_readfirstlane_b32 s13, v7
	v_readfirstlane_b32 s12, v6
	v_readfirstlane_b32 s8, v9
	v_readfirstlane_b32 s9, v8
	v_readfirstlane_b32 s17, v11
	v_readfirstlane_b32 s16, v10
	v_readfirstlane_b32 s10, v13
	v_readfirstlane_b32 s11, v12
	v_readfirstlane_b32 s18, v15
	v_readfirstlane_b32 s19, v14
	v_readfirstlane_b32 s7, v17
	v_readfirstlane_b32 s6, v16
	s_cbranch_vccnz .LBB0_400
	v_readlane_b32 s28, v255, 52
	v_readlane_b32 s29, v255, 53
	s_add_u32 s6, s6, 0x22f00000
	s_mul_i32 s22, s29, 0x2100
	s_mul_hi_u32 s23, s28, 0x2100
	s_addc_u32 s7, s7, 0
	s_lshl_b64 s[20:21], s[28:29], 14
	s_add_i32 s24, s23, s22
	s_lshl_b32 s30, s30, 8
	s_add_u32 s22, s19, s30
	s_addc_u32 s23, s18, 0
	s_add_u32 s18, s11, s30
	s_addc_u32 s19, s10, 0
	s_mul_i32 s27, s28, 0x2100
	s_add_u32 s28, s9, s30
	s_addc_u32 s29, s8, 0
	v_and_b32_e32 v16, 63, v4
	s_add_u32 s30, s1, s30
	v_lshlrev_b32_e32 v184, 2, v16
	s_addc_u32 s31, s0, 0
	v_add_u32_e32 v0, -1, v4
	v_and_b32_e32 v0, 15, v0
	v_lshl_add_u64 v[6:7], s[18:19], 0, v[184:185]
	s_add_u32 s18, s15, s27
	v_ashrrev_i32_e32 v17, 6, v4
	v_cvt_f32_ubyte0_e32 v0, v0
	v_mov_b32_e32 v1, 0x38d1b717
	s_movk_i32 s34, 0x90
	v_lshlrev_b32_e32 v10, 2, v4
	s_addc_u32 s19, s14, s24
	v_or_b32_e32 v12, s20, v184
	v_mov_b32_e32 v13, s21
	v_add_u32_e32 v14, 0, v184
	v_fmamk_f32 v18, v0, 0x3f7fff90, v1
	v_mul_lo_u32 v15, v17, s34
	v_lshl_add_u64 v[0:1], s[30:31], 0, v[184:185]
	v_lshl_add_u64 v[2:3], s[22:23], 0, v[184:185]
	v_add_u32_e32 v20, 0, v10
	v_lshl_add_u64 v[4:5], s[28:29], 0, v[184:185]
	v_lshl_add_u64 v[8:9], s[18:19], 0, v[184:185]
	s_mov_b64 s[18:19], 0x200
	v_and_b32_e32 v22, 0xffffff00, v10
	s_add_i32 s14, 0, 0x480
	v_lshl_add_u64 v[10:11], s[12:13], 0, v[12:13]
	v_readlane_b32 s12, v255, 37
	v_lshl_add_u64 v[12:13], s[16:17], 0, v[12:13]
	s_mov_b32 s22, 0x6dc9c883
	s_mov_b32 s28, 0x54442d18
	s_mov_b32 s30, 0xf6dcf572
	v_cmp_gt_u32_e64 s[0:1], 33, v16
	v_cmp_ne_u32_e64 s[8:9], 0, v16
	v_cmp_lt_u32_e64 s[10:11], 16, v16
	v_add_u32_e32 v19, 0, v15
	v_lshl_add_u64 v[8:9], v[8:9], 0, s[18:19]
	v_add_u32_e32 v21, s14, v22
	v_lshl_add_u64 v[10:11], v[10:11], 0, s[18:19]
	v_add_u32_e32 v22, s12, v22
	v_lshl_add_u64 v[12:13], v[12:13], 0, s[18:19]
	v_add_u32_e32 v23, v14, v15
	s_mov_b32 s14, s2
	s_mov_b32 s23, 0x3fc45f30
	s_mov_b32 s29, 0xc01921fb
	s_mov_b32 s31, 0xbbd71b8e
